# lazy rescale + tile-32 key masking moved out of line + partner-lane address hoisted out of the tile loop (paged MLA attention compute waves)
# speedup vs baseline: 1.0141x; 1.0002x over previous
.LBB0_1358:
	s_or_b64 exec, exec, s[0:1]
	s_cmp_eq_u32 s97, 7
	v_and_b32_e32 v168, 63, v1
	s_cselect_b32 s62, 33, 32
	s_waitcnt lgkmcnt(0)
	s_barrier
	s_and_saveexec_b64 s[0:1], s[14:15]
	s_xor_b64 s[0:1], exec, s[0:1]
	s_cbranch_execz .LBB0_1366
	s_mov_b32 s8, 0x55555556
	v_mul_hi_i32 v3, v186, s8
	v_lshrrev_b32_e32 v4, 31, v3
	s_waitcnt vmcnt(18)
	v_add_u32_e32 v164, v3, v4
	v_lshl_add_u32 v3, v164, 1, v164
	v_sub_u32_e32 v3, v186, v3
	v_lshl_or_b32 v162, v3, 5, v178
	s_mov_b32 s8, 0x2aaaaaab
	v_mul_hi_i32 v3, v162, s8
	v_lshrrev_b32_e32 v4, 31, v3
	v_ashrrev_i32_e32 v3, 1, v3
	v_add_u32_e32 v3, v3, v4
	v_mul_lo_u32 v4, v3, 12
	v_sub_u32_e32 v4, v162, v4
	s_add_i32 s8, 0, 0x20600
	v_add_u32_e32 v5, 2, v186
	v_lshl_add_u32 v163, v4, 2, s8
	v_lshlrev_b32_e32 v4, 5, v164
	v_cmp_gt_u32_e32 vcc, 5, v5
	v_or_b32_e32 v5, v4, v178
	v_mul_lo_u32 v165, v5, s33
	v_mul_lo_u32 v5, v162, s33
	v_add_u32_e32 v18, 0, v5
	v_or_b32_e32 v4, v173, v4
	v_lshrrev_b32_e32 v5, 2, v1
	v_lshlrev_b32_e32 v6, 1, v1
	v_lshlrev_b32_e32 v1, 3, v1
	v_min_i32_e32 v3, 7, v3
	v_and_b32_e32 v169, 24, v1
	v_or_b32_e32 v1, 2, v4
	v_cmp_gt_i32_e64 s[18:19], v1, v3
	v_or_b32_e32 v1, 3, v4
	v_cmp_gt_i32_e64 s[20:21], v1, v3
	v_or_b32_e32 v1, 8, v4
	v_cmp_gt_i32_e64 s[22:23], v1, v3
	v_or_b32_e32 v1, 9, v4
	v_cmp_gt_i32_e64 s[24:25], v1, v3
	v_or_b32_e32 v1, 10, v4
	v_cmp_gt_i32_e64 s[26:27], v1, v3
	v_or_b32_e32 v1, 11, v4
	v_cmp_gt_i32_e64 s[28:29], v1, v3
	v_or_b32_e32 v1, 16, v4
	v_cmp_gt_i32_e64 s[30:31], v1, v3
	v_or_b32_e32 v1, 17, v4
	v_cmp_gt_i32_e64 s[34:35], v1, v3
	v_or_b32_e32 v1, 18, v4
	v_cmp_gt_i32_e64 s[36:37], v1, v3
	v_or_b32_e32 v1, 19, v4
	v_cmp_gt_i32_e64 s[38:39], v1, v3
	v_or_b32_e32 v1, 24, v4
	v_cmp_gt_i32_e64 s[40:41], v1, v3
	v_or_b32_e32 v1, 25, v4
	v_cmp_gt_i32_e64 s[42:43], v1, v3
	v_or_b32_e32 v1, 26, v4
	v_and_or_b32 v5, v5, 3, v4
	v_cmp_gt_i32_e64 s[44:45], v1, v3
	v_or_b32_e32 v1, 27, v4
	v_mov_b32_e32 v16, v2
	v_mov_b32_e32 v17, v2
	v_and_b32_e32 v167, 32, v6
	v_mul_lo_u32 v170, v4, 48
	v_cmp_gt_i32_e64 s[14:15], v4, v3
	v_cmp_ge_i32_e64 s[16:17], v4, v3
	v_cmp_gt_i32_e64 s[46:47], v1, v3
	v_mul_lo_u32 v171, v5, s33
	v_mov_b32_e32 v3, v2
	v_mov_b32_e32 v4, v2
	v_mov_b32_e32 v5, v2
	v_mov_b32_e32 v6, v2
	v_mov_b32_e32 v7, v2
	v_mov_b32_e32 v8, v2
	v_mov_b32_e32 v9, v2
	v_mov_b32_e32 v10, v2
	v_mov_b32_e32 v11, v2
	v_mov_b32_e32 v12, v2
	v_mov_b32_e32 v13, v2
	v_mov_b32_e32 v14, v2
	v_mov_b32_e32 v15, v2
	v_add_u32_e32 v173, v18, v172
	s_waitcnt vmcnt(14)
	v_mov_b64_e32 v[32:33], v[16:17]
	s_waitcnt vmcnt(10)
	v_mov_b64_e32 v[48:49], v[16:17]
	s_waitcnt vmcnt(0)
	v_mov_b64_e32 v[64:65], v[16:17]
	v_mov_b64_e32 v[80:81], v[16:17]
	v_mov_b64_e32 v[96:97], v[16:17]
	v_mov_b64_e32 v[112:113], v[16:17]
	v_mov_b64_e32 v[128:129], v[16:17]
	v_mov_b64_e32 v[144:145], v[16:17]
	s_mov_b32 s64, 0
	v_mov_b32_e32 v166, 0xf149f2ca
	v_mov_b32_e32 v1, 0
	v_mov_b64_e32 v[30:31], v[14:15]
	v_mov_b64_e32 v[28:29], v[12:13]
	v_mov_b64_e32 v[26:27], v[10:11]
	v_mov_b64_e32 v[24:25], v[8:9]
	v_mov_b64_e32 v[22:23], v[6:7]
	v_mov_b64_e32 v[20:21], v[4:5]
	v_mov_b64_e32 v[18:19], v[2:3]
	v_mov_b64_e32 v[46:47], v[14:15]
	v_mov_b64_e32 v[44:45], v[12:13]
	v_mov_b64_e32 v[42:43], v[10:11]
	v_mov_b64_e32 v[40:41], v[8:9]
	v_mov_b64_e32 v[38:39], v[6:7]
	v_mov_b64_e32 v[36:37], v[4:5]
	v_mov_b64_e32 v[34:35], v[2:3]
	v_mov_b64_e32 v[62:63], v[14:15]
	v_mov_b64_e32 v[60:61], v[12:13]
	v_mov_b64_e32 v[58:59], v[10:11]
	v_mov_b64_e32 v[56:57], v[8:9]
	v_mov_b64_e32 v[54:55], v[6:7]
	v_mov_b64_e32 v[52:53], v[4:5]
	v_mov_b64_e32 v[50:51], v[2:3]
	v_mov_b64_e32 v[78:79], v[14:15]
	v_mov_b64_e32 v[76:77], v[12:13]
	v_mov_b64_e32 v[74:75], v[10:11]
	v_mov_b64_e32 v[72:73], v[8:9]
	v_mov_b64_e32 v[70:71], v[6:7]
	v_mov_b64_e32 v[68:69], v[4:5]
	v_mov_b64_e32 v[66:67], v[2:3]
	v_mov_b64_e32 v[94:95], v[14:15]
	v_mov_b64_e32 v[92:93], v[12:13]
	v_mov_b64_e32 v[90:91], v[10:11]
	v_mov_b64_e32 v[88:89], v[8:9]
	v_mov_b64_e32 v[86:87], v[6:7]
	v_mov_b64_e32 v[84:85], v[4:5]
	v_mov_b64_e32 v[82:83], v[2:3]
	v_mov_b64_e32 v[110:111], v[14:15]
	v_mov_b64_e32 v[108:109], v[12:13]
	v_mov_b64_e32 v[106:107], v[10:11]
	v_mov_b64_e32 v[104:105], v[8:9]
	v_mov_b64_e32 v[102:103], v[6:7]
	v_mov_b64_e32 v[100:101], v[4:5]
	v_mov_b64_e32 v[98:99], v[2:3]
	v_mov_b64_e32 v[126:127], v[14:15]
	v_mov_b64_e32 v[124:125], v[12:13]
	v_mov_b64_e32 v[122:123], v[10:11]
	v_mov_b64_e32 v[120:121], v[8:9]
	v_mov_b64_e32 v[118:119], v[6:7]
	v_mov_b64_e32 v[116:117], v[4:5]
	v_mov_b64_e32 v[114:115], v[2:3]
	v_mov_b64_e32 v[142:143], v[14:15]
	v_mov_b64_e32 v[140:141], v[12:13]
	v_mov_b64_e32 v[138:139], v[10:11]
	v_mov_b64_e32 v[136:137], v[8:9]
	v_mov_b64_e32 v[134:135], v[6:7]
	v_mov_b64_e32 v[132:133], v[4:5]
	v_mov_b64_e32 v[130:131], v[2:3]
	v_and_b32_e32 v252, 64, v236
	v_xor_b32_e32 v239, 32, v236
	v_add_u32_e32 v252, 64, v252
	v_cmp_lt_i32_e64 s[100:101], v239, v252
	s_nop 1
	v_cndmask_b32_e64 v252, v236, v239, s[100:101]
	v_lshlrev_b32_e32 v252, 2, v252
	s_branch .LBB0_1361

.LBB0_1361:
	s_cmp_lt_u32 s64, 32
	s_cselect_b64 s[8:9], -1, 0
	s_or_b64 s[48:49], s[8:9], vcc
	s_and_saveexec_b64 s[8:9], s[48:49]
	s_cbranch_execz .LBB0_1360
	s_and_b32 s48, s64, 1
	s_mul_i32 s49, s48, 0x9400
	s_add_i32 s65, s49, 0
	v_add3_u32 v3, s65, v165, v172
	ds_read_b128 v[4:7], v3 offset:56832
	ds_read_b128 v[8:11], v173
	ds_read_b128 v[12:15], v173 offset:32
	ds_read_b128 v[176:179], v3 offset:56864
	s_waitcnt lgkmcnt(2)
	v_mfma_f32_32x32x16_bf16 v[146:161], v[4:7], v[8:11], 0
	s_mulk_i32 s48, 0xc00
	v_add3_u32 v175, v163, s48, v170
	s_cmp_eq_u32 s64, 32
	s_cselect_b64 s[54:55], -1, 0
	s_waitcnt lgkmcnt(0)
	v_mfma_f32_32x32x16_bf16 v[146:161], v[176:179], v[12:15], v[146:161]
	ds_read_b128 v[4:7], v3 offset:56896
	ds_read_b128 v[8:11], v173 offset:64
	ds_read_b128 v[12:15], v173 offset:96
	ds_read_b128 v[176:179], v3 offset:56928
	s_waitcnt lgkmcnt(2)
	v_mfma_f32_32x32x16_bf16 v[146:161], v[4:7], v[8:11], v[146:161]
	s_waitcnt lgkmcnt(0)
	v_mfma_f32_32x32x16_bf16 v[146:161], v[176:179], v[12:15], v[146:161]
	ds_read_b128 v[4:7], v3 offset:56960
	ds_read_b128 v[8:11], v173 offset:128
	ds_read_b128 v[12:15], v173 offset:160
	ds_read_b128 v[176:179], v3 offset:56992
	s_waitcnt lgkmcnt(2)
	v_mfma_f32_32x32x16_bf16 v[146:161], v[4:7], v[8:11], v[146:161]
	s_waitcnt lgkmcnt(0)
	v_mfma_f32_32x32x16_bf16 v[146:161], v[176:179], v[12:15], v[146:161]
	ds_read_b128 v[4:7], v3 offset:57024
	ds_read_b128 v[8:11], v173 offset:192
	ds_read_b128 v[12:15], v173 offset:224
	ds_read_b128 v[176:179], v3 offset:57056
	s_waitcnt lgkmcnt(2)
	v_mfma_f32_32x32x16_bf16 v[146:161], v[4:7], v[8:11], v[146:161]
	s_waitcnt lgkmcnt(0)
	v_mfma_f32_32x32x16_bf16 v[146:161], v[176:179], v[12:15], v[146:161]
	ds_read_b128 v[4:7], v3 offset:57088
	ds_read_b128 v[8:11], v173 offset:256
	ds_read_b128 v[12:15], v173 offset:288
	ds_read_b128 v[176:179], v3 offset:57120
	s_waitcnt lgkmcnt(2)
	v_mfma_f32_32x32x16_bf16 v[146:161], v[4:7], v[8:11], v[146:161]
	s_waitcnt lgkmcnt(0)
	v_mfma_f32_32x32x16_bf16 v[146:161], v[176:179], v[12:15], v[146:161]
	ds_read_b128 v[4:7], v3 offset:57152
	ds_read_b128 v[8:11], v173 offset:320
	ds_read_b128 v[12:15], v173 offset:352
	ds_read_b128 v[176:179], v3 offset:57184
	s_waitcnt lgkmcnt(2)
	v_mfma_f32_32x32x16_bf16 v[146:161], v[4:7], v[8:11], v[146:161]
	s_waitcnt lgkmcnt(0)
	v_mfma_f32_32x32x16_bf16 v[146:161], v[176:179], v[12:15], v[146:161]
	ds_read_b128 v[4:7], v3 offset:57216
	ds_read_b128 v[8:11], v173 offset:384
	ds_read_b128 v[12:15], v173 offset:416
	ds_read_b128 v[176:179], v3 offset:57248
	s_waitcnt lgkmcnt(2)
	v_mfma_f32_32x32x16_bf16 v[146:161], v[4:7], v[8:11], v[146:161]
	s_waitcnt lgkmcnt(0)
	v_mfma_f32_32x32x16_bf16 v[146:161], v[176:179], v[12:15], v[146:161]
	ds_read_b128 v[4:7], v3 offset:57280
	ds_read_b128 v[8:11], v173 offset:448
	ds_read_b128 v[12:15], v173 offset:480
	ds_read_b128 v[176:179], v3 offset:57312
	s_waitcnt lgkmcnt(2)
	v_mfma_f32_32x32x16_bf16 v[146:161], v[4:7], v[8:11], v[146:161]
	ds_read_b128 v[4:7], v173 offset:512
	ds_read_b128 v[8:11], v173 offset:544
	ds_read_b128 v[180:183], v3 offset:57344
	s_waitcnt lgkmcnt(3)
	v_mfma_f32_32x32x16_bf16 v[146:161], v[176:179], v[12:15], v[146:161]
	ds_read2_b32 v[16:17], v175 offset1:12
	ds_read2_b32 v[176:177], v175 offset0:24 offset1:36
	ds_read2_b32 v[178:179], v175 offset0:96 offset1:108
	ds_read2_b32 v[184:185], v175 offset0:120 offset1:132
	ds_read_b128 v[12:15], v3 offset:57376
	v_add_u32_e32 v3, 0x400, v175
	s_waitcnt lgkmcnt(5)
	v_mfma_f32_32x32x16_bf16 v[146:161], v[180:183], v[4:7], v[146:161]
	ds_read2_b32 v[4:5], v175 offset0:192 offset1:204
	ds_read2_b32 v[6:7], v175 offset0:216 offset1:228
	ds_read2_b32 v[180:181], v3 offset0:32 offset1:44
	ds_read2_b32 v[182:183], v3 offset0:56 offset1:68
	s_waitcnt lgkmcnt(4)
	v_mfma_f32_32x32x16_bf16 v[146:161], v[12:15], v[8:11], v[146:161]
	s_nop 11
	v_mul_f32_e32 v3, v146, v16
	v_mul_f32_e32 v8, v17, v147
	v_mul_f32_e32 v9, v176, v148
	v_mul_f32_e32 v10, v177, v149
	v_mul_f32_e32 v11, v178, v150
	v_mul_f32_e32 v12, v179, v151
	v_mul_f32_e32 v13, v184, v152
	v_mul_f32_e32 v14, v185, v153
	s_waitcnt lgkmcnt(3)
	v_mul_f32_e32 v4, v4, v154
	v_mul_f32_e32 v5, v5, v155
	s_waitcnt lgkmcnt(2)
	v_mul_f32_e32 v6, v6, v156
	v_mul_f32_e32 v7, v7, v157
	s_waitcnt lgkmcnt(1)
	v_mul_f32_e32 v15, v180, v158
	v_mul_f32_e32 v16, v181, v159
	s_waitcnt lgkmcnt(0)
	v_mul_f32_e32 v17, v182, v160
	v_mul_f32_e32 v146, v183, v161
	s_cmp_eq_u32 s64, 32
	s_cbranch_scc1 .LmaskA
	v_mov_b32_e32 v147, v3
.LmaskA_join:
	v_max_f32_e32 v3, v147, v8
	v_max3_f32 v3, v3, v9, v10
	v_max3_f32 v3, v3, v11, v12
	v_max3_f32 v3, v3, v13, v14
	v_max3_f32 v3, v3, v4, v5
	v_max3_f32 v3, v3, v6, v7
	v_max3_f32 v3, v3, v15, v16
	v_max3_f32 v3, v3, v17, v146
	ds_bpermute_b32 v148, v252, v3
	s_waitcnt lgkmcnt(0)
	v_max_f32_e32 v148, v3, v148
	v_mov_b32_e32 v233, 0x41000000
	v_sub_f32_e32 v3, v148, v166
	v_cmp_lt_f32_e64 s[100:101], v233, v3
	s_cmp_lg_u64 s[100:101], 0
	s_cbranch_scc1 .LlazyA_rescale
	v_mov_b32_e32 v3, v166
	v_mov_b32_e32 v148, 0

.LmaskA:
	s_and_b64 s[48:49], s[14:15], s[54:55]
	v_cndmask_b32_e64 v147, v3, v238, s[48:49]
	s_and_b64 s[48:49], s[16:17], s[54:55]
	v_cndmask_b32_e64 v8, v8, v238, s[48:49]
	s_and_b64 s[48:49], s[18:19], s[54:55]
	v_cndmask_b32_e64 v9, v9, v238, s[48:49]
	s_and_b64 s[48:49], s[20:21], s[54:55]
	v_cndmask_b32_e64 v10, v10, v238, s[48:49]
	s_and_b64 s[48:49], s[22:23], s[54:55]
	v_cndmask_b32_e64 v11, v11, v238, s[48:49]
	s_and_b64 s[48:49], s[24:25], s[54:55]
	v_cndmask_b32_e64 v12, v12, v238, s[48:49]
	s_and_b64 s[48:49], s[26:27], s[54:55]
	v_cndmask_b32_e64 v13, v13, v238, s[48:49]
	s_and_b64 s[48:49], s[28:29], s[54:55]
	v_cndmask_b32_e64 v14, v14, v238, s[48:49]
	s_and_b64 s[48:49], s[30:31], s[54:55]
	v_cndmask_b32_e64 v4, v4, v238, s[48:49]
	s_and_b64 s[48:49], s[34:35], s[54:55]
	v_cndmask_b32_e64 v5, v5, v238, s[48:49]
	s_and_b64 s[48:49], s[36:37], s[54:55]
	v_cndmask_b32_e64 v6, v6, v238, s[48:49]
	s_and_b64 s[48:49], s[38:39], s[54:55]
	v_cndmask_b32_e64 v7, v7, v238, s[48:49]
	s_and_b64 s[48:49], s[40:41], s[54:55]
	v_cndmask_b32_e64 v15, v15, v238, s[48:49]
	s_and_b64 s[48:49], s[42:43], s[54:55]
	v_cndmask_b32_e64 v16, v16, v238, s[48:49]
	s_and_b64 s[48:49], s[44:45], s[54:55]
	v_cndmask_b32_e64 v17, v17, v238, s[48:49]
	s_and_b64 s[48:49], s[46:47], s[54:55]
	v_cndmask_b32_e64 v146, v146, v238, s[48:49]
	s_branch .LmaskA_join

.LBB0_1540:
	s_or_b64 exec, exec, s[0:1]
	s_cmp_eq_u32 s94, 7
	v_and_b32_e32 v168, 63, v1
	s_cselect_b32 s64, 33, 32
	s_waitcnt lgkmcnt(0)
	s_barrier
	s_and_saveexec_b64 s[0:1], s[14:15]
	s_xor_b64 s[0:1], exec, s[0:1]
	s_cbranch_execz .LBB0_1548
	s_mov_b32 s8, 0x55555556
	v_mul_hi_i32 v3, v186, s8
	v_lshrrev_b32_e32 v4, 31, v3
	s_waitcnt vmcnt(18)
	v_add_u32_e32 v164, v3, v4
	v_lshl_add_u32 v3, v164, 1, v164
	v_sub_u32_e32 v3, v186, v3
	v_lshl_or_b32 v162, v3, 5, v178
	s_mov_b32 s8, 0x2aaaaaab
	v_mul_hi_i32 v3, v162, s8
	v_lshrrev_b32_e32 v4, 31, v3
	v_ashrrev_i32_e32 v3, 1, v3
	v_add_u32_e32 v3, v3, v4
	v_mul_lo_u32 v4, v3, 12
	v_sub_u32_e32 v4, v162, v4
	s_add_i32 s8, 0, 0x20600
	v_add_u32_e32 v5, 2, v186
	v_lshl_add_u32 v163, v4, 2, s8
	v_lshlrev_b32_e32 v4, 5, v164
	v_cmp_gt_u32_e32 vcc, 5, v5
	v_or_b32_e32 v5, v4, v178
	v_mul_lo_u32 v165, v5, s33
	v_mul_lo_u32 v5, v162, s33
	v_add_u32_e32 v18, 0, v5
	v_or_b32_e32 v4, v173, v4
	v_lshrrev_b32_e32 v5, 2, v1
	v_lshlrev_b32_e32 v6, 1, v1
	v_lshlrev_b32_e32 v1, 3, v1
	v_min_i32_e32 v3, 7, v3
	v_and_b32_e32 v169, 24, v1
	v_or_b32_e32 v1, 2, v4
	v_cmp_gt_i32_e64 s[18:19], v1, v3
	v_or_b32_e32 v1, 3, v4
	v_cmp_gt_i32_e64 s[20:21], v1, v3
	v_or_b32_e32 v1, 8, v4
	v_cmp_gt_i32_e64 s[22:23], v1, v3
	v_or_b32_e32 v1, 9, v4
	v_cmp_gt_i32_e64 s[24:25], v1, v3
	v_or_b32_e32 v1, 10, v4
	v_cmp_gt_i32_e64 s[26:27], v1, v3
	v_or_b32_e32 v1, 11, v4
	v_cmp_gt_i32_e64 s[28:29], v1, v3
	v_or_b32_e32 v1, 16, v4
	v_cmp_gt_i32_e64 s[30:31], v1, v3
	v_or_b32_e32 v1, 17, v4
	v_cmp_gt_i32_e64 s[34:35], v1, v3
	v_or_b32_e32 v1, 18, v4
	v_cmp_gt_i32_e64 s[36:37], v1, v3
	v_or_b32_e32 v1, 19, v4
	v_cmp_gt_i32_e64 s[38:39], v1, v3
	v_or_b32_e32 v1, 24, v4
	v_cmp_gt_i32_e64 s[40:41], v1, v3
	v_or_b32_e32 v1, 25, v4
	v_cmp_gt_i32_e64 s[42:43], v1, v3
	v_or_b32_e32 v1, 26, v4
	v_and_or_b32 v5, v5, 3, v4
	v_cmp_gt_i32_e64 s[44:45], v1, v3
	v_or_b32_e32 v1, 27, v4
	v_mov_b32_e32 v16, v2
	v_mov_b32_e32 v17, v2
	v_and_b32_e32 v167, 32, v6
	v_mul_lo_u32 v170, v4, 48
	v_cmp_gt_i32_e64 s[14:15], v4, v3
	v_cmp_ge_i32_e64 s[16:17], v4, v3
	v_cmp_gt_i32_e64 s[46:47], v1, v3
	v_mul_lo_u32 v171, v5, s33
	v_mov_b32_e32 v3, v2
	v_mov_b32_e32 v4, v2
	v_mov_b32_e32 v5, v2
	v_mov_b32_e32 v6, v2
	v_mov_b32_e32 v7, v2
	v_mov_b32_e32 v8, v2
	v_mov_b32_e32 v9, v2
	v_mov_b32_e32 v10, v2
	v_mov_b32_e32 v11, v2
	v_mov_b32_e32 v12, v2
	v_mov_b32_e32 v13, v2
	v_mov_b32_e32 v14, v2
	v_mov_b32_e32 v15, v2
	v_add_u32_e32 v173, v18, v172
	s_waitcnt vmcnt(14)
	v_mov_b64_e32 v[32:33], v[16:17]
	s_waitcnt vmcnt(10)
	v_mov_b64_e32 v[48:49], v[16:17]
	s_waitcnt vmcnt(0)
	v_mov_b64_e32 v[64:65], v[16:17]
	v_mov_b64_e32 v[80:81], v[16:17]
	v_mov_b64_e32 v[96:97], v[16:17]
	v_mov_b64_e32 v[112:113], v[16:17]
	v_mov_b64_e32 v[128:129], v[16:17]
	v_mov_b64_e32 v[144:145], v[16:17]
	s_mov_b32 s65, 0
	v_mov_b32_e32 v166, 0xf149f2ca
	v_mov_b32_e32 v1, 0
	v_mov_b64_e32 v[30:31], v[14:15]
	v_mov_b64_e32 v[28:29], v[12:13]
	v_mov_b64_e32 v[26:27], v[10:11]
	v_mov_b64_e32 v[24:25], v[8:9]
	v_mov_b64_e32 v[22:23], v[6:7]
	v_mov_b64_e32 v[20:21], v[4:5]
	v_mov_b64_e32 v[18:19], v[2:3]
	v_mov_b64_e32 v[46:47], v[14:15]
	v_mov_b64_e32 v[44:45], v[12:13]
	v_mov_b64_e32 v[42:43], v[10:11]
	v_mov_b64_e32 v[40:41], v[8:9]
	v_mov_b64_e32 v[38:39], v[6:7]
	v_mov_b64_e32 v[36:37], v[4:5]
	v_mov_b64_e32 v[34:35], v[2:3]
	v_mov_b64_e32 v[62:63], v[14:15]
	v_mov_b64_e32 v[60:61], v[12:13]
	v_mov_b64_e32 v[58:59], v[10:11]
	v_mov_b64_e32 v[56:57], v[8:9]
	v_mov_b64_e32 v[54:55], v[6:7]
	v_mov_b64_e32 v[52:53], v[4:5]
	v_mov_b64_e32 v[50:51], v[2:3]
	v_mov_b64_e32 v[78:79], v[14:15]
	v_mov_b64_e32 v[76:77], v[12:13]
	v_mov_b64_e32 v[74:75], v[10:11]
	v_mov_b64_e32 v[72:73], v[8:9]
	v_mov_b64_e32 v[70:71], v[6:7]
	v_mov_b64_e32 v[68:69], v[4:5]
	v_mov_b64_e32 v[66:67], v[2:3]
	v_mov_b64_e32 v[94:95], v[14:15]
	v_mov_b64_e32 v[92:93], v[12:13]
	v_mov_b64_e32 v[90:91], v[10:11]
	v_mov_b64_e32 v[88:89], v[8:9]
	v_mov_b64_e32 v[86:87], v[6:7]
	v_mov_b64_e32 v[84:85], v[4:5]
	v_mov_b64_e32 v[82:83], v[2:3]
	v_mov_b64_e32 v[110:111], v[14:15]
	v_mov_b64_e32 v[108:109], v[12:13]
	v_mov_b64_e32 v[106:107], v[10:11]
	v_mov_b64_e32 v[104:105], v[8:9]
	v_mov_b64_e32 v[102:103], v[6:7]
	v_mov_b64_e32 v[100:101], v[4:5]
	v_mov_b64_e32 v[98:99], v[2:3]
	v_mov_b64_e32 v[126:127], v[14:15]
	v_mov_b64_e32 v[124:125], v[12:13]
	v_mov_b64_e32 v[122:123], v[10:11]
	v_mov_b64_e32 v[120:121], v[8:9]
	v_mov_b64_e32 v[118:119], v[6:7]
	v_mov_b64_e32 v[116:117], v[4:5]
	v_mov_b64_e32 v[114:115], v[2:3]
	v_mov_b64_e32 v[142:143], v[14:15]
	v_mov_b64_e32 v[140:141], v[12:13]
	v_mov_b64_e32 v[138:139], v[10:11]
	v_mov_b64_e32 v[136:137], v[8:9]
	v_mov_b64_e32 v[134:135], v[6:7]
	v_mov_b64_e32 v[132:133], v[4:5]
	v_mov_b64_e32 v[130:131], v[2:3]
	v_and_b32_e32 v252, 64, v236
	v_xor_b32_e32 v239, 32, v236
	v_add_u32_e32 v252, 64, v252
	v_cmp_lt_i32_e64 s[100:101], v239, v252
	s_nop 1
	v_cndmask_b32_e64 v252, v236, v239, s[100:101]
	v_lshlrev_b32_e32 v252, 2, v252
	s_branch .LBB0_1543

.LBB0_1543:
	s_cmp_lt_u32 s65, 32
	s_cselect_b64 s[8:9], -1, 0
	s_or_b64 s[48:49], s[8:9], vcc
	s_and_saveexec_b64 s[8:9], s[48:49]
	s_cbranch_execz .LBB0_1542
	s_and_b32 s48, s65, 1
	s_mul_i32 s49, s48, 0x9400
	s_add_i32 s67, s49, 0
	v_add3_u32 v3, s67, v165, v172
	ds_read_b128 v[4:7], v3 offset:56832
	ds_read_b128 v[8:11], v173
	ds_read_b128 v[12:15], v173 offset:32
	ds_read_b128 v[176:179], v3 offset:56864
	s_waitcnt lgkmcnt(2)
	v_mfma_f32_32x32x16_bf16 v[146:161], v[4:7], v[8:11], 0
	s_mulk_i32 s48, 0xc00
	v_add3_u32 v175, v163, s48, v170
	s_cmp_eq_u32 s65, 32
	s_cselect_b64 s[74:75], -1, 0
	s_waitcnt lgkmcnt(0)
	v_mfma_f32_32x32x16_bf16 v[146:161], v[176:179], v[12:15], v[146:161]
	ds_read_b128 v[4:7], v3 offset:56896
	ds_read_b128 v[8:11], v173 offset:64
	ds_read_b128 v[12:15], v173 offset:96
	ds_read_b128 v[176:179], v3 offset:56928
	s_waitcnt lgkmcnt(2)
	v_mfma_f32_32x32x16_bf16 v[146:161], v[4:7], v[8:11], v[146:161]
	s_waitcnt lgkmcnt(0)
	v_mfma_f32_32x32x16_bf16 v[146:161], v[176:179], v[12:15], v[146:161]
	ds_read_b128 v[4:7], v3 offset:56960
	ds_read_b128 v[8:11], v173 offset:128
	ds_read_b128 v[12:15], v173 offset:160
	ds_read_b128 v[176:179], v3 offset:56992
	s_waitcnt lgkmcnt(2)
	v_mfma_f32_32x32x16_bf16 v[146:161], v[4:7], v[8:11], v[146:161]
	s_waitcnt lgkmcnt(0)
	v_mfma_f32_32x32x16_bf16 v[146:161], v[176:179], v[12:15], v[146:161]
	ds_read_b128 v[4:7], v3 offset:57024
	ds_read_b128 v[8:11], v173 offset:192
	ds_read_b128 v[12:15], v173 offset:224
	ds_read_b128 v[176:179], v3 offset:57056
	s_waitcnt lgkmcnt(2)
	v_mfma_f32_32x32x16_bf16 v[146:161], v[4:7], v[8:11], v[146:161]
	s_waitcnt lgkmcnt(0)
	v_mfma_f32_32x32x16_bf16 v[146:161], v[176:179], v[12:15], v[146:161]
	ds_read_b128 v[4:7], v3 offset:57088
	ds_read_b128 v[8:11], v173 offset:256
	ds_read_b128 v[12:15], v173 offset:288
	ds_read_b128 v[176:179], v3 offset:57120
	s_waitcnt lgkmcnt(2)
	v_mfma_f32_32x32x16_bf16 v[146:161], v[4:7], v[8:11], v[146:161]
	s_waitcnt lgkmcnt(0)
	v_mfma_f32_32x32x16_bf16 v[146:161], v[176:179], v[12:15], v[146:161]
	ds_read_b128 v[4:7], v3 offset:57152
	ds_read_b128 v[8:11], v173 offset:320
	ds_read_b128 v[12:15], v173 offset:352
	ds_read_b128 v[176:179], v3 offset:57184
	s_waitcnt lgkmcnt(2)
	v_mfma_f32_32x32x16_bf16 v[146:161], v[4:7], v[8:11], v[146:161]
	s_waitcnt lgkmcnt(0)
	v_mfma_f32_32x32x16_bf16 v[146:161], v[176:179], v[12:15], v[146:161]
	ds_read_b128 v[4:7], v3 offset:57216
	ds_read_b128 v[8:11], v173 offset:384
	ds_read_b128 v[12:15], v173 offset:416
	ds_read_b128 v[176:179], v3 offset:57248
	s_waitcnt lgkmcnt(2)
	v_mfma_f32_32x32x16_bf16 v[146:161], v[4:7], v[8:11], v[146:161]
	s_waitcnt lgkmcnt(0)
	v_mfma_f32_32x32x16_bf16 v[146:161], v[176:179], v[12:15], v[146:161]
	ds_read_b128 v[4:7], v3 offset:57280
	ds_read_b128 v[8:11], v173 offset:448
	ds_read_b128 v[12:15], v173 offset:480
	ds_read_b128 v[176:179], v3 offset:57312
	s_waitcnt lgkmcnt(2)
	v_mfma_f32_32x32x16_bf16 v[146:161], v[4:7], v[8:11], v[146:161]
	ds_read_b128 v[4:7], v173 offset:512
	ds_read_b128 v[8:11], v173 offset:544
	ds_read_b128 v[180:183], v3 offset:57344
	s_waitcnt lgkmcnt(3)
	v_mfma_f32_32x32x16_bf16 v[146:161], v[176:179], v[12:15], v[146:161]
	ds_read2_b32 v[16:17], v175 offset1:12
	ds_read2_b32 v[176:177], v175 offset0:24 offset1:36
	ds_read2_b32 v[178:179], v175 offset0:96 offset1:108
	ds_read2_b32 v[184:185], v175 offset0:120 offset1:132
	ds_read_b128 v[12:15], v3 offset:57376
	v_add_u32_e32 v3, 0x400, v175
	s_waitcnt lgkmcnt(5)
	v_mfma_f32_32x32x16_bf16 v[146:161], v[180:183], v[4:7], v[146:161]
	ds_read2_b32 v[4:5], v175 offset0:192 offset1:204
	ds_read2_b32 v[6:7], v175 offset0:216 offset1:228
	ds_read2_b32 v[180:181], v3 offset0:32 offset1:44
	ds_read2_b32 v[182:183], v3 offset0:56 offset1:68
	s_waitcnt lgkmcnt(4)
	v_mfma_f32_32x32x16_bf16 v[146:161], v[12:15], v[8:11], v[146:161]
	s_nop 11
	v_mul_f32_e32 v3, v146, v16
	v_mul_f32_e32 v8, v17, v147
	v_mul_f32_e32 v9, v176, v148
	v_mul_f32_e32 v10, v177, v149
	v_mul_f32_e32 v11, v178, v150
	v_mul_f32_e32 v12, v179, v151
	v_mul_f32_e32 v13, v184, v152
	v_mul_f32_e32 v14, v185, v153
	s_waitcnt lgkmcnt(3)
	v_mul_f32_e32 v4, v4, v154
	v_mul_f32_e32 v5, v5, v155
	s_waitcnt lgkmcnt(2)
	v_mul_f32_e32 v6, v6, v156
	v_mul_f32_e32 v7, v7, v157
	s_waitcnt lgkmcnt(1)
	v_mul_f32_e32 v15, v180, v158
	v_mul_f32_e32 v16, v181, v159
	s_waitcnt lgkmcnt(0)
	v_mul_f32_e32 v17, v182, v160
	v_mul_f32_e32 v146, v183, v161
	s_cmp_eq_u32 s65, 32
	s_cbranch_scc1 .LmaskB
	v_mov_b32_e32 v147, v3

.LmaskB:
	s_and_b64 s[48:49], s[14:15], s[74:75]
	v_cndmask_b32_e64 v147, v3, v238, s[48:49]
	s_and_b64 s[48:49], s[16:17], s[74:75]
	v_cndmask_b32_e64 v8, v8, v238, s[48:49]
	s_and_b64 s[48:49], s[18:19], s[74:75]
	v_cndmask_b32_e64 v9, v9, v238, s[48:49]
	s_and_b64 s[48:49], s[20:21], s[74:75]
	v_cndmask_b32_e64 v10, v10, v238, s[48:49]
	s_and_b64 s[48:49], s[22:23], s[74:75]
	v_cndmask_b32_e64 v11, v11, v238, s[48:49]
	s_and_b64 s[48:49], s[24:25], s[74:75]
	v_cndmask_b32_e64 v12, v12, v238, s[48:49]
	s_and_b64 s[48:49], s[26:27], s[74:75]
	v_cndmask_b32_e64 v13, v13, v238, s[48:49]
	s_and_b64 s[48:49], s[28:29], s[74:75]
	v_cndmask_b32_e64 v14, v14, v238, s[48:49]
	s_and_b64 s[48:49], s[30:31], s[74:75]
	v_cndmask_b32_e64 v4, v4, v238, s[48:49]
	s_and_b64 s[48:49], s[34:35], s[74:75]
	v_cndmask_b32_e64 v5, v5, v238, s[48:49]
	s_and_b64 s[48:49], s[36:37], s[74:75]
	v_cndmask_b32_e64 v6, v6, v238, s[48:49]
	s_and_b64 s[48:49], s[38:39], s[74:75]
	v_cndmask_b32_e64 v7, v7, v238, s[48:49]
	s_and_b64 s[48:49], s[40:41], s[74:75]
	v_cndmask_b32_e64 v15, v15, v238, s[48:49]
	s_and_b64 s[48:49], s[42:43], s[74:75]
	v_cndmask_b32_e64 v16, v16, v238, s[48:49]
	s_and_b64 s[48:49], s[44:45], s[74:75]
	v_cndmask_b32_e64 v17, v17, v238, s[48:49]
	s_and_b64 s[48:49], s[46:47], s[74:75]
	v_cndmask_b32_e64 v146, v146, v238, s[48:49]
	s_branch .LmaskB_join
	s_nop 0
	s_nop 0
	s_nop 0
	s_nop 0
	s_nop 0
	s_nop 0
	s_nop 0
	s_nop 0
	s_nop 0
	s_nop 0
	s_nop 0
	s_nop 0
	s_nop 0
	s_nop 0
	s_nop 0
	s_nop 0
	s_nop 0
	s_nop 0
	s_nop 0
	s_nop 0
	s_nop 0
	s_nop 0
	s_nop 0
	s_nop 0
	s_nop 0
	s_nop 0
	s_nop 0
	s_nop 0
	s_nop 0
	s_nop 0
